# GEMM tile preheaders: accumulator zeroing with 64 v_mov_b64 instead of 127 v_mov_b32
# speedup vs baseline: 1.0043x; 1.0043x over previous
; template <class Epi>
; __device__ __forceinline__ void gemm_phase(LAS unsigned char* lds, const Gemm g, const StaticOrder& S, const Epi& E) {
;     ...
;         const char* nA = has_next ? (const char*)g.A + (size_t)nxt.pm * tA : cA; const char* nB = has_next ? (const char*)g.Bt + (size_t)nxt.pn * tB : cB;
;         for (int t = 0; t < nt; t += 2) {
;     ...
;         for (int a = 0; a < 2; ++a)
; #pragma unroll
;             for (int b = 0; b < 2; ++b)
; #pragma unroll
;                 for (int m = 0; m < 4; ++m)
; #pragma unroll
;                     for (int n = 0; n < 2; ++n) acc[a][b][m][n] = (f32x4){0.f, 0.f, 0.f, 0.f};
.LBB0_131:
	s_ashr_i32 s27, s26, 31
	s_lshl_b64 s[28:29], s[26:27], 19
	s_add_u32 s28, s54, s28
	s_addc_u32 s29, s55, s29
	s_and_b64 s[30:31], s[36:37], exec
	s_cselect_b32 s7, s29, s9
	s_cselect_b32 s27, s28, s8
	s_ashr_i32 s25, s24, 31
	s_lshl_b64 s[30:31], s[24:25], 19
	s_add_u32 s30, s52, s30
	s_addc_u32 s31, s53, s31
	s_and_b64 s[36:37], s[36:37], exec
	s_cselect_b32 s25, s31, s35
	s_cselect_b32 s38, s30, s34
	s_add_u32 s8, s8, 0x40080
	s_addc_u32 s9, s9, 0
	s_add_u32 s39, s34, 0x100
	v_mov_b64_e32 v[2:3], 0
	v_mov_b64_e32 v[4:5], 0
	v_mov_b64_e32 v[6:7], 0
	v_mov_b64_e32 v[8:9], 0
	v_mov_b64_e32 v[10:11], 0
	v_mov_b64_e32 v[12:13], 0
	v_mov_b64_e32 v[14:15], 0
	v_mov_b64_e32 v[16:17], 0
	v_mov_b64_e32 v[18:19], 0
	v_mov_b64_e32 v[20:21], 0
	v_mov_b64_e32 v[22:23], 0
	v_mov_b64_e32 v[24:25], 0
	v_mov_b64_e32 v[26:27], 0
	v_mov_b64_e32 v[28:29], 0
	v_mov_b64_e32 v[30:31], 0
	v_mov_b64_e32 v[32:33], 0
	v_mov_b64_e32 v[34:35], 0
	v_mov_b64_e32 v[36:37], 0
	v_mov_b64_e32 v[38:39], 0
	v_mov_b64_e32 v[40:41], 0
	v_mov_b64_e32 v[42:43], 0
	v_mov_b64_e32 v[44:45], 0
	v_mov_b64_e32 v[46:47], 0
	v_mov_b64_e32 v[48:49], 0
	v_mov_b64_e32 v[50:51], 0
	v_mov_b64_e32 v[52:53], 0
	v_mov_b64_e32 v[54:55], 0
	v_mov_b64_e32 v[56:57], 0
	v_mov_b64_e32 v[58:59], 0
	v_mov_b64_e32 v[60:61], 0
	v_mov_b64_e32 v[62:63], 0
	v_mov_b64_e32 v[64:65], 0
	v_mov_b64_e32 v[66:67], 0
	v_mov_b64_e32 v[68:69], 0
	v_mov_b64_e32 v[70:71], 0
	v_mov_b64_e32 v[72:73], 0
	v_mov_b64_e32 v[74:75], 0
	v_mov_b64_e32 v[76:77], 0
	v_mov_b64_e32 v[78:79], 0
	v_mov_b64_e32 v[80:81], 0
	v_mov_b64_e32 v[82:83], 0
	v_mov_b64_e32 v[84:85], 0
	v_mov_b64_e32 v[86:87], 0
	v_mov_b64_e32 v[88:89], 0
	v_mov_b64_e32 v[90:91], 0
	v_mov_b64_e32 v[92:93], 0
	v_mov_b64_e32 v[94:95], 0
	v_mov_b64_e32 v[96:97], 0
	v_mov_b64_e32 v[98:99], 0
	v_mov_b64_e32 v[100:101], 0
	v_mov_b64_e32 v[102:103], 0
	v_mov_b64_e32 v[104:105], 0
	v_mov_b64_e32 v[106:107], 0
	v_mov_b64_e32 v[108:109], 0
	v_mov_b64_e32 v[110:111], 0
	v_mov_b64_e32 v[112:113], 0
	v_mov_b64_e32 v[114:115], 0
	v_mov_b64_e32 v[116:117], 0
	v_mov_b64_e32 v[118:119], 0
	v_mov_b64_e32 v[120:121], 0
	v_mov_b64_e32 v[122:123], 0
	v_mov_b64_e32 v[124:125], 0
	v_mov_b64_e32 v[126:127], 0
	v_mov_b64_e32 v[128:129], 0
	s_addc_u32 s40, s35, 0
	s_mov_b32 s41, -2

; template <class Epi>
; __device__ __forceinline__ void gemm_phase(LAS unsigned char* lds, const Gemm g, const StaticOrder& S, const Epi& E) {
;     ...
;         const char* nA = has_next ? (const char*)g.A + (size_t)nxt.pm * tA : cA; const char* nB = has_next ? (const char*)g.Bt + (size_t)nxt.pn * tB : cB;
;         for (int t = 0; t < nt; t += 2) {
;     ...
;         for (int a = 0; a < 2; ++a)
; #pragma unroll
;             for (int b = 0; b < 2; ++b)
; #pragma unroll
;                 for (int m = 0; m < 4; ++m)
; #pragma unroll
;                     for (int n = 0; n < 2; ++n) acc[a][b][m][n] = (f32x4){0.f, 0.f, 0.f, 0.f};
.LBB0_1397:
	s_ashr_i32 s35, s34, 31
	s_lshl_b64 s[36:37], s[34:35], 19
	s_add_u32 s27, s46, s36
	s_addc_u32 s29, s47, s37
	s_and_b64 s[36:37], s[38:39], exec
	s_cselect_b32 s37, s29, s9
	s_cselect_b32 s36, s27, s8
	s_ashr_i32 s31, s30, 31
	s_lshl_b64 s[40:41], s[30:31], 19
	s_add_u32 s27, s48, s40
	s_addc_u32 s29, s49, s41
	s_and_b64 s[38:39], s[38:39], exec
	s_cselect_b32 s39, s29, s11
	s_cselect_b32 s38, s27, s10
	s_add_u32 s8, s8, 0x40080
	s_addc_u32 s9, s9, 0
	s_add_u32 s27, s10, 0x100
	v_mov_b64_e32 v[2:3], 0
	v_mov_b64_e32 v[4:5], 0
	v_mov_b64_e32 v[6:7], 0
	v_mov_b64_e32 v[8:9], 0
	v_mov_b64_e32 v[10:11], 0
	v_mov_b64_e32 v[12:13], 0
	v_mov_b64_e32 v[14:15], 0
	v_mov_b64_e32 v[16:17], 0
	v_mov_b64_e32 v[18:19], 0
	v_mov_b64_e32 v[20:21], 0
	v_mov_b64_e32 v[22:23], 0
	v_mov_b64_e32 v[24:25], 0
	v_mov_b64_e32 v[26:27], 0
	v_mov_b64_e32 v[28:29], 0
	v_mov_b64_e32 v[30:31], 0
	v_mov_b64_e32 v[32:33], 0
	v_mov_b64_e32 v[34:35], 0
	v_mov_b64_e32 v[36:37], 0
	v_mov_b64_e32 v[38:39], 0
	v_mov_b64_e32 v[40:41], 0
	v_mov_b64_e32 v[42:43], 0
	v_mov_b64_e32 v[44:45], 0
	v_mov_b64_e32 v[46:47], 0
	v_mov_b64_e32 v[48:49], 0
	v_mov_b64_e32 v[50:51], 0
	v_mov_b64_e32 v[52:53], 0
	v_mov_b64_e32 v[54:55], 0
	v_mov_b64_e32 v[56:57], 0
	v_mov_b64_e32 v[58:59], 0
	v_mov_b64_e32 v[60:61], 0
	v_mov_b64_e32 v[62:63], 0
	v_mov_b64_e32 v[64:65], 0
	v_mov_b64_e32 v[66:67], 0
	v_mov_b64_e32 v[68:69], 0
	v_mov_b64_e32 v[70:71], 0
	v_mov_b64_e32 v[72:73], 0
	v_mov_b64_e32 v[74:75], 0
	v_mov_b64_e32 v[76:77], 0
	v_mov_b64_e32 v[78:79], 0
	v_mov_b64_e32 v[80:81], 0
	v_mov_b64_e32 v[82:83], 0
	v_mov_b64_e32 v[84:85], 0
	v_mov_b64_e32 v[86:87], 0
	v_mov_b64_e32 v[88:89], 0
	v_mov_b64_e32 v[90:91], 0
	v_mov_b64_e32 v[92:93], 0
	v_mov_b64_e32 v[94:95], 0
	v_mov_b64_e32 v[96:97], 0
	v_mov_b64_e32 v[98:99], 0
	v_mov_b64_e32 v[100:101], 0
	v_mov_b64_e32 v[102:103], 0
	v_mov_b64_e32 v[104:105], 0
	v_mov_b64_e32 v[106:107], 0
	v_mov_b64_e32 v[108:109], 0
	v_mov_b64_e32 v[110:111], 0
	v_mov_b64_e32 v[112:113], 0
	v_mov_b64_e32 v[114:115], 0
	v_mov_b64_e32 v[116:117], 0
	v_mov_b64_e32 v[118:119], 0
	v_mov_b64_e32 v[120:121], 0
	v_mov_b64_e32 v[122:123], 0
	v_mov_b64_e32 v[124:125], 0
	v_mov_b64_e32 v[126:127], 0
	v_mov_b64_e32 v[128:129], 0
	s_addc_u32 s29, s11, 0
	s_mov_b32 s31, -2
	s_waitcnt lgkmcnt(0)

; template <class Epi>
; __device__ __forceinline__ void gemm_phase(LAS unsigned char* lds, const Gemm g, const StaticOrder& S, const Epi& E) {
;     ...
;         const char* nA = has_next ? (const char*)g.A + (size_t)nxt.pm * tA : cA; const char* nB = has_next ? (const char*)g.Bt + (size_t)nxt.pn * tB : cB;
;         for (int t = 0; t < nt; t += 2) {
;     ...
;         for (int a = 0; a < 2; ++a)
; #pragma unroll
;             for (int b = 0; b < 2; ++b)
; #pragma unroll
;                 for (int m = 0; m < 4; ++m)
; #pragma unroll
;                     for (int n = 0; n < 2; ++n) acc[a][b][m][n] = (f32x4){0.f, 0.f, 0.f, 0.f};
.LBB0_1549:
	s_ashr_i32 s15, s14, 31
	s_lshl_b64 s[16:17], s[14:15], 19
	s_add_u32 s16, s27, s16
	s_addc_u32 s17, s28, s17
	s_and_b64 s[18:19], s[24:25], exec
	s_cselect_b32 s15, s17, s21
	s_cselect_b32 s46, s16, s20
	s_ashr_i32 s13, s12, 31
	s_lshl_b64 s[18:19], s[12:13], 19
	s_add_u32 s18, s29, s18
	s_addc_u32 s19, s30, s19
	s_and_b64 s[24:25], s[24:25], exec
	s_cselect_b32 s13, s19, s23
	s_cselect_b32 s47, s18, s22
	s_add_u32 s20, s20, 0x40080
	s_addc_u32 s21, s21, 0
	s_add_u32 s48, s22, 0x100
	v_mov_b64_e32 v[2:3], 0
	v_mov_b64_e32 v[4:5], 0
	v_mov_b64_e32 v[6:7], 0
	v_mov_b64_e32 v[8:9], 0
	v_mov_b64_e32 v[10:11], 0
	v_mov_b64_e32 v[12:13], 0
	v_mov_b64_e32 v[14:15], 0
	v_mov_b64_e32 v[16:17], 0
	v_mov_b64_e32 v[18:19], 0
	v_mov_b64_e32 v[20:21], 0
	v_mov_b64_e32 v[22:23], 0
	v_mov_b64_e32 v[24:25], 0
	v_mov_b64_e32 v[26:27], 0
	v_mov_b64_e32 v[28:29], 0
	v_mov_b64_e32 v[30:31], 0
	v_mov_b64_e32 v[32:33], 0
	v_mov_b64_e32 v[34:35], 0
	v_mov_b64_e32 v[36:37], 0
	v_mov_b64_e32 v[38:39], 0
	v_mov_b64_e32 v[40:41], 0
	v_mov_b64_e32 v[42:43], 0
	v_mov_b64_e32 v[44:45], 0
	v_mov_b64_e32 v[46:47], 0
	v_mov_b64_e32 v[48:49], 0
	v_mov_b64_e32 v[50:51], 0
	v_mov_b64_e32 v[52:53], 0
	v_mov_b64_e32 v[54:55], 0
	v_mov_b64_e32 v[56:57], 0
	v_mov_b64_e32 v[58:59], 0
	v_mov_b64_e32 v[60:61], 0
	v_mov_b64_e32 v[62:63], 0
	v_mov_b64_e32 v[64:65], 0
	v_mov_b64_e32 v[66:67], 0
	v_mov_b64_e32 v[68:69], 0
	v_mov_b64_e32 v[70:71], 0
	v_mov_b64_e32 v[72:73], 0
	v_mov_b64_e32 v[74:75], 0
	v_mov_b64_e32 v[76:77], 0
	v_mov_b64_e32 v[78:79], 0
	v_mov_b64_e32 v[80:81], 0
	v_mov_b64_e32 v[82:83], 0
	v_mov_b64_e32 v[84:85], 0
	v_mov_b64_e32 v[86:87], 0
	v_mov_b64_e32 v[88:89], 0
	v_mov_b64_e32 v[90:91], 0
	v_mov_b64_e32 v[92:93], 0
	v_mov_b64_e32 v[94:95], 0
	v_mov_b64_e32 v[96:97], 0
	v_mov_b64_e32 v[98:99], 0
	v_mov_b64_e32 v[100:101], 0
	v_mov_b64_e32 v[102:103], 0
	v_mov_b64_e32 v[104:105], 0
	v_mov_b64_e32 v[106:107], 0
	v_mov_b64_e32 v[108:109], 0
	v_mov_b64_e32 v[110:111], 0
	v_mov_b64_e32 v[112:113], 0
	v_mov_b64_e32 v[114:115], 0
	v_mov_b64_e32 v[116:117], 0
	v_mov_b64_e32 v[118:119], 0
	v_mov_b64_e32 v[120:121], 0
	v_mov_b64_e32 v[122:123], 0
	v_mov_b64_e32 v[124:125], 0
	v_mov_b64_e32 v[126:127], 0
	v_mov_b64_e32 v[128:129], 0
	s_addc_u32 s49, s23, 0
	s_mov_b32 s50, -2

; template <class Epi>
; __device__ __forceinline__ void gemm_phase(LAS unsigned char* lds, const Gemm g, const StaticOrder& S, const Epi& E) {
;     ...
;         for (int a = 0; a < 2; ++a)
; #pragma unroll
;             for (int b = 0; b < 2; ++b)
; #pragma unroll
;                 for (int m = 0; m < 4; ++m)
; #pragma unroll
;                     for (int n = 0; n < 2; ++n) acc[a][b][m][n] = (f32x4){0.f, 0.f, 0.f, 0.f};
;         cur = nxt; cA = nA; cB = nB; ++ui;
.LBB0_1631:
	s_add_u32 s35, s42, 0x100
	v_mov_b64_e32 v[2:3], 0
	v_mov_b64_e32 v[4:5], 0
	v_mov_b64_e32 v[6:7], 0
	v_mov_b64_e32 v[8:9], 0
	v_mov_b64_e32 v[10:11], 0
	v_mov_b64_e32 v[12:13], 0
	v_mov_b64_e32 v[14:15], 0
	v_mov_b64_e32 v[16:17], 0
	v_mov_b64_e32 v[18:19], 0
	v_mov_b64_e32 v[20:21], 0
	v_mov_b64_e32 v[22:23], 0
	v_mov_b64_e32 v[24:25], 0
	v_mov_b64_e32 v[26:27], 0
	v_mov_b64_e32 v[28:29], 0
	v_mov_b64_e32 v[30:31], 0
	v_mov_b64_e32 v[32:33], 0
	v_mov_b64_e32 v[34:35], 0
	v_mov_b64_e32 v[36:37], 0
	v_mov_b64_e32 v[38:39], 0
	v_mov_b64_e32 v[40:41], 0
	v_mov_b64_e32 v[42:43], 0
	v_mov_b64_e32 v[44:45], 0
	v_mov_b64_e32 v[46:47], 0
	v_mov_b64_e32 v[48:49], 0
	v_mov_b64_e32 v[50:51], 0
	v_mov_b64_e32 v[52:53], 0
	v_mov_b64_e32 v[54:55], 0
	v_mov_b64_e32 v[56:57], 0
	v_mov_b64_e32 v[58:59], 0
	v_mov_b64_e32 v[60:61], 0
	v_mov_b64_e32 v[62:63], 0
	v_mov_b64_e32 v[64:65], 0
	v_mov_b64_e32 v[66:67], 0
	v_mov_b64_e32 v[68:69], 0
	v_mov_b64_e32 v[70:71], 0
	v_mov_b64_e32 v[72:73], 0
	v_mov_b64_e32 v[74:75], 0
	v_mov_b64_e32 v[76:77], 0
	v_mov_b64_e32 v[78:79], 0
	v_mov_b64_e32 v[80:81], 0
	v_mov_b64_e32 v[82:83], 0
	v_mov_b64_e32 v[84:85], 0
	v_mov_b64_e32 v[86:87], 0
	v_mov_b64_e32 v[88:89], 0
	v_mov_b64_e32 v[90:91], 0
	v_mov_b64_e32 v[92:93], 0
	v_mov_b64_e32 v[94:95], 0
	v_mov_b64_e32 v[96:97], 0
	v_mov_b64_e32 v[98:99], 0
	v_mov_b64_e32 v[100:101], 0
	v_mov_b64_e32 v[102:103], 0
	v_mov_b64_e32 v[104:105], 0
	v_mov_b64_e32 v[106:107], 0
	v_mov_b64_e32 v[108:109], 0
	v_mov_b64_e32 v[110:111], 0
	v_mov_b64_e32 v[112:113], 0
	v_mov_b64_e32 v[114:115], 0
	v_mov_b64_e32 v[116:117], 0
	v_mov_b64_e32 v[118:119], 0
	v_mov_b64_e32 v[120:121], 0
	v_mov_b64_e32 v[122:123], 0
	v_mov_b64_e32 v[124:125], 0
	v_mov_b64_e32 v[126:127], 0
	v_mov_b64_e32 v[128:129], 0
	s_addc_u32 s37, s43, 0
	s_mov_b32 s67, -2
